# split-barrier wait: acquire L1 invalidate issued before the poll loop instead of after it
# speedup vs baseline: 1.0172x; 1.0011x over previous
; __device__ __forceinline__ int lane_now() { int l; asm volatile("v_mbcnt_lo_u32_b32 %0, -1, 0\n\tv_mbcnt_hi_u32_b32 %0, -1, %0" : "=v"(l)); return l; }
; __device__ __forceinline__ unsigned xb_ld(unsigned* p)              { return __hip_atomic_load(p, __ATOMIC_RELAXED, __HIP_MEMORY_SCOPE_AGENT); }
; __device__ __forceinline__ void xcd_barrier_wait(const XcdBarrier& b) {
;     ...
;         unsigned* bar = b.bar; unsigned lane = (unsigned)lane_now();
;         __builtin_amdgcn_s_waitcnt(0);
;         const unsigned mask = (unsigned)__builtin_amdgcn_readfirstlane((int)b.st[1]), tgt = (unsigned)__builtin_amdgcn_readfirstlane((int)b.st[2]);
;         const bool grp = b.st[4] != 0u;
;         const bool mine = grp ? lane == 0u : (lane < 16u && ((mask >> lane) & 1u) != 0u);
;         unsigned g = b.x; asm volatile("" : "+s"(g));
;         unsigned* slot = &bar[grp ? XB_GTOP(g) : XB_TOP + lane];
;         unsigned sp = 0u;
;         for (;;) {
;             const unsigned v = mine ? xb_ld(slot) : 0xFFFFFFFFu;
;             if (__builtin_amdgcn_ballot_w64(v < tgt) == 0ull) break;
.LBB0_40:
	s_mov_b32 s8, s33
	s_lshl_b32 s8, s8, 6
	s_addk_i32 s8, 0x1200
	v_add_u32_e32 v0, 0xd00, v2
	v_mov_b32_e32 v1, s8
	v_cndmask_b32_e64 v32, v1, v0, s[6:7]
	v_readlane_b32 s6, v251, 4
	v_readlane_b32 s7, v251, 5
	s_mov_b32 s19, 1
	s_nop 0
	v_lshl_add_u64 v[0:1], v[32:33], 2, s[6:7]
	v_cmp_eq_u32_e64 s[6:7], 0, v2
	buffer_inv sc1
	s_branch .LBB0_42

; __device__ __forceinline__ void xcd_barrier_wait(const XcdBarrier& b) {
;     ...
;         __builtin_amdgcn_fence(__ATOMIC_ACQUIRE, "agent");
;         asm volatile("s_waitcnt vmcnt(0)" ::: "memory");
;     }
;     __syncthreads();
.LBB0_116:
	s_waitcnt vmcnt(0)
	s_waitcnt vmcnt(0)
	v_readlane_b32 s18, v254, 40
	s_mov_b32 s36, s18
	v_readlane_b32 s19, v254, 41
